# plus grid barrier: non-leader workgroups poll the top-level generation word directly (one flag hop less per barrier)
# speedup vs baseline: 1.0034x; 1.0034x over previous
.LBB0_136:
	s_or_b64 exec, exec, s[10:11]
	v_cvt_f32_u32_e32 v5, v3
	s_waitcnt vmcnt(0)
	v_readfirstlane_b32 s8, v4
	v_sub_u32_e32 v4, 0, v3
	v_rcp_iflag_f32_e32 v5, v5
	v_add_u32_e32 v6, s8, v2
	v_mul_f32_e32 v5, 0x4f7ffffe, v5
	v_cvt_u32_f32_e32 v5, v5
	v_mul_lo_u32 v2, v4, v5
	v_mul_hi_u32 v2, v5, v2
	v_add_u32_e32 v2, v5, v2
	v_mul_hi_u32 v2, v6, v2
	v_mul_lo_u32 v4, v2, v3
	v_sub_u32_e32 v4, v6, v4
	v_add_u32_e32 v5, 1, v2
	v_cmp_ge_u32_e32 vcc, v4, v3
	s_nop 1
	v_cndmask_b32_e32 v2, v2, v5, vcc
	v_sub_u32_e32 v5, v4, v3
	v_cndmask_b32_e32 v4, v4, v5, vcc
	v_add_u32_e32 v5, 1, v2
	v_cmp_ge_u32_e32 vcc, v4, v3
	v_add_u32_e32 v4, 1, v6
	s_nop 0
	v_cndmask_b32_e32 v2, v2, v5, vcc
	v_mul_lo_u32 v5, v3, v2
	v_add_u32_e32 v3, v5, v3
	v_cmp_ne_u32_e32 vcc, v4, v3
	s_and_saveexec_b64 s[8:9], vcc
	s_xor_b64 s[8:9], exec, s[8:9]
	s_cbranch_execz .LBB0_150
	s_waitcnt lgkmcnt(0)
	v_mov_b32_e32 v1, 0x3100
	global_load_dword v1, v1, s[28:29] offset:1024 sc1
	s_add_u32 s12, s28, 0x3500
	s_addc_u32 s13, s29, 0
	s_waitcnt vmcnt(0)
	v_cmp_eq_u32_e32 vcc, v1, v2
	s_and_saveexec_b64 s[10:11], vcc
	s_cbranch_execz .LBB0_149
	s_mov_b32 s26, 1
	s_mov_b64 s[16:17], 0
	v_mov_b32_e32 v1, 0
	s_branch .LBB0_140

.LBB0_1505:
	s_or_b64 exec, exec, s[10:11]
	v_cvt_f32_u32_e32 v5, v3
	s_waitcnt vmcnt(0)
	v_readfirstlane_b32 s3, v4
	v_sub_u32_e32 v4, 0, v3
	v_rcp_iflag_f32_e32 v5, v5
	v_add_u32_e32 v6, s3, v2
	v_mul_f32_e32 v5, 0x4f7ffffe, v5
	v_cvt_u32_f32_e32 v5, v5
	v_mul_lo_u32 v2, v4, v5
	v_mul_hi_u32 v2, v5, v2
	v_add_u32_e32 v2, v5, v2
	v_mul_hi_u32 v2, v6, v2
	v_mul_lo_u32 v4, v2, v3
	v_sub_u32_e32 v4, v6, v4
	v_add_u32_e32 v5, 1, v2
	v_cmp_ge_u32_e32 vcc, v4, v3
	s_nop 1
	v_cndmask_b32_e32 v2, v2, v5, vcc
	v_sub_u32_e32 v5, v4, v3
	v_cndmask_b32_e32 v4, v4, v5, vcc
	v_add_u32_e32 v5, 1, v2
	v_cmp_ge_u32_e32 vcc, v4, v3
	v_add_u32_e32 v4, 1, v6
	s_nop 0
	v_cndmask_b32_e32 v2, v2, v5, vcc
	v_mul_lo_u32 v5, v3, v2
	v_add_u32_e32 v3, v5, v3
	v_cmp_ne_u32_e32 vcc, v4, v3
	s_and_saveexec_b64 s[8:9], vcc
	s_xor_b64 s[8:9], exec, s[8:9]
	s_cbranch_execz .LBB0_1519
	s_waitcnt lgkmcnt(0)
	v_mov_b32_e32 v1, 0x3100
	global_load_dword v1, v1, s[28:29] offset:1024 sc1
	s_add_u32 s12, s28, 0x3500
	s_addc_u32 s13, s29, 0
	s_waitcnt vmcnt(0)
	v_cmp_eq_u32_e32 vcc, v1, v2
	s_and_saveexec_b64 s[10:11], vcc
	s_cbranch_execz .LBB0_1518
	s_mov_b32 s3, 1
	s_mov_b64 s[14:15], 0
	v_mov_b32_e32 v1, 0
	s_branch .LBB0_1509
